# P0: waves not converting weights run a hand-written 8-rows-in-flight x->XB bf16/RSS pass (role split)
# speedup vs baseline: 1.0597x; 1.0067x over previous
; #define KIN(i) ((const float*)kptr<float>(i))
; __global__ void __launch_bounds__(NWAVES * 64, 2) fwd_mega(Args args) {
;     ...
;         { const float* x_prompt = KIN(0); const float* x_sample = KIN(1); bf16_t* XB = (bf16_t*)(ws + WS_XB); float* RSS = (float*)(ws + WS_RSS);
;         for (int m0 = gw; m0 < MT; m0 += 3 * NGW) {
;             f32x4 v[3][4];
; #pragma unroll
;             for (int i = 0; i < 3; ++i) { const int m = m0 + i * NGW; if (m < MT) { const float* src = m < TP ? x_prompt + (size_t)m * DM : x_sample + (size_t)(m - TP) * DM;
; #pragma unroll
;                 for (int j = 0; j < 4; ++j) v[i][j] = __builtin_nontemporal_load((const f32x4*)(src + 4 * lane + 256 * j)); } }
.LBB0_43:
	s_load_dwordx2 s[12:13], s[0:1], 0x0
	s_load_dwordx2 s[14:15], s[0:1], 0x8
	s_waitcnt lgkmcnt(0)
	s_add_u32 s2, s10, 0x5500000
	s_addc_u32 s3, s11, 0
	s_cmpk_gt_i32 s26, 0x41ff
	s_mov_b32 s76, s94
	s_cbranch_scc1 .LBB0_60
	s_cmpk_lt_u32 s82, 0x700
	s_cbranch_scc1 .Lx_nosplit
	s_cmpk_lt_i32 s26, 0x380
	s_cbranch_scc1 .LBB0_60
	s_sub_i32 s26, s26, 0x380
	s_sub_i32 s82, s82, 0x380
	v_and_b32_e32 v132, 63, v74
	v_lshlrev_b32_e32 v133, 3, v132
	v_lshlrev_b32_e32 v132, 4, v132
	v_mov_b32_e32 v134, 0
.Lxb_batch:
	s_cmpk_gt_i32 s26, 0x41ff
	s_cbranch_scc1 .Lxb_done
	s_mov_b32 s4, s26
	s_cmpk_gt_i32 s4, 0x41ff
	s_cbranch_scc1 .Lxb_ld_done
	s_sub_i32 s5, s4, 0x4000
	s_cmpk_lt_i32 s4, 0x4000
	s_cselect_b32 s16, s12, s14
	s_cselect_b32 s17, s13, s15
	s_cselect_b32 s5, s4, s5
	s_lshl_b32 s5, s5, 12
	s_add_u32 s16, s16, s5
	s_addc_u32 s17, s17, 0
	global_load_dwordx4 v[0:3], v132, s[16:17] nt
	global_load_dwordx4 v[4:7], v132, s[16:17] offset:1024 nt
	global_load_dwordx4 v[8:11], v132, s[16:17] offset:2048 nt
	global_load_dwordx4 v[12:15], v132, s[16:17] offset:3072 nt
	s_add_i32 s4, s4, s82
	s_cmpk_gt_i32 s4, 0x41ff
	s_cbranch_scc1 .Lxb_ld_done
	s_sub_i32 s5, s4, 0x4000
	s_cmpk_lt_i32 s4, 0x4000
	s_cselect_b32 s16, s12, s14
	s_cselect_b32 s17, s13, s15
	s_cselect_b32 s5, s4, s5
	s_lshl_b32 s5, s5, 12
	s_add_u32 s16, s16, s5
	s_addc_u32 s17, s17, 0
	global_load_dwordx4 v[16:19], v132, s[16:17] nt
	global_load_dwordx4 v[20:23], v132, s[16:17] offset:1024 nt
	global_load_dwordx4 v[24:27], v132, s[16:17] offset:2048 nt
	global_load_dwordx4 v[28:31], v132, s[16:17] offset:3072 nt
	s_add_i32 s4, s4, s82
	s_cmpk_gt_i32 s4, 0x41ff
	s_cbranch_scc1 .Lxb_ld_done
	s_sub_i32 s5, s4, 0x4000
	s_cmpk_lt_i32 s4, 0x4000
	s_cselect_b32 s16, s12, s14
	s_cselect_b32 s17, s13, s15
	s_cselect_b32 s5, s4, s5
	s_lshl_b32 s5, s5, 12
	s_add_u32 s16, s16, s5
	s_addc_u32 s17, s17, 0
	global_load_dwordx4 v[32:35], v132, s[16:17] nt
	global_load_dwordx4 v[36:39], v132, s[16:17] offset:1024 nt
	global_load_dwordx4 v[40:43], v132, s[16:17] offset:2048 nt
	global_load_dwordx4 v[44:47], v132, s[16:17] offset:3072 nt
	s_add_i32 s4, s4, s82
	s_cmpk_gt_i32 s4, 0x41ff
	s_cbranch_scc1 .Lxb_ld_done
	s_sub_i32 s5, s4, 0x4000
	s_cmpk_lt_i32 s4, 0x4000
	s_cselect_b32 s16, s12, s14
	s_cselect_b32 s17, s13, s15
	s_cselect_b32 s5, s4, s5
	s_lshl_b32 s5, s5, 12
	s_add_u32 s16, s16, s5
	s_addc_u32 s17, s17, 0
	global_load_dwordx4 v[48:51], v132, s[16:17] nt
	global_load_dwordx4 v[52:55], v132, s[16:17] offset:1024 nt
	global_load_dwordx4 v[56:59], v132, s[16:17] offset:2048 nt
	global_load_dwordx4 v[60:63], v132, s[16:17] offset:3072 nt
	s_add_i32 s4, s4, s82
	s_cmpk_gt_i32 s4, 0x41ff
	s_cbranch_scc1 .Lxb_ld_done
	s_sub_i32 s5, s4, 0x4000
	s_cmpk_lt_i32 s4, 0x4000
	s_cselect_b32 s16, s12, s14
	s_cselect_b32 s17, s13, s15
	s_cselect_b32 s5, s4, s5
	s_lshl_b32 s5, s5, 12
	s_add_u32 s16, s16, s5
	s_addc_u32 s17, s17, 0
	global_load_dwordx4 v[64:67], v132, s[16:17] nt
	global_load_dwordx4 v[68:71], v132, s[16:17] offset:1024 nt
	global_load_dwordx4 v[76:79], v132, s[16:17] offset:2048 nt
	global_load_dwordx4 v[80:83], v132, s[16:17] offset:3072 nt
	s_add_i32 s4, s4, s82
	s_cmpk_gt_i32 s4, 0x41ff
	s_cbranch_scc1 .Lxb_ld_done
	s_sub_i32 s5, s4, 0x4000
	s_cmpk_lt_i32 s4, 0x4000
	s_cselect_b32 s16, s12, s14
	s_cselect_b32 s17, s13, s15
	s_cselect_b32 s5, s4, s5
	s_lshl_b32 s5, s5, 12
	s_add_u32 s16, s16, s5
	s_addc_u32 s17, s17, 0
	global_load_dwordx4 v[84:87], v132, s[16:17] nt
	global_load_dwordx4 v[88:91], v132, s[16:17] offset:1024 nt
	global_load_dwordx4 v[92:95], v132, s[16:17] offset:2048 nt
	global_load_dwordx4 v[96:99], v132, s[16:17] offset:3072 nt
	s_add_i32 s4, s4, s82
	s_cmpk_gt_i32 s4, 0x41ff
	s_cbranch_scc1 .Lxb_ld_done
	s_sub_i32 s5, s4, 0x4000
	s_cmpk_lt_i32 s4, 0x4000
	s_cselect_b32 s16, s12, s14
	s_cselect_b32 s17, s13, s15
	s_cselect_b32 s5, s4, s5
	s_lshl_b32 s5, s5, 12
	s_add_u32 s16, s16, s5
	s_addc_u32 s17, s17, 0
	global_load_dwordx4 v[100:103], v132, s[16:17] nt
	global_load_dwordx4 v[104:107], v132, s[16:17] offset:1024 nt
	global_load_dwordx4 v[108:111], v132, s[16:17] offset:2048 nt
	global_load_dwordx4 v[112:115], v132, s[16:17] offset:3072 nt
	s_add_i32 s4, s4, s82
	s_cmpk_gt_i32 s4, 0x41ff
	s_cbranch_scc1 .Lxb_ld_done
	s_sub_i32 s5, s4, 0x4000
	s_cmpk_lt_i32 s4, 0x4000
	s_cselect_b32 s16, s12, s14
	s_cselect_b32 s17, s13, s15
	s_cselect_b32 s5, s4, s5
	s_lshl_b32 s5, s5, 12
	s_add_u32 s16, s16, s5
	s_addc_u32 s17, s17, 0
	global_load_dwordx4 v[116:119], v132, s[16:17] nt
	global_load_dwordx4 v[120:123], v132, s[16:17] offset:1024 nt
	global_load_dwordx4 v[124:127], v132, s[16:17] offset:2048 nt
	global_load_dwordx4 v[128:131], v132, s[16:17] offset:3072 nt
	s_add_i32 s4, s4, s82
; __device__ __forceinline__ unsigned pk2(float lo, float hi) { f32x2 v = {lo, hi}; bf16x2_t b = __builtin_convertvector(v, bf16x2_t); return __builtin_bit_cast(unsigned, b); }
; __global__ void __launch_bounds__(NWAVES * 64, 2) fwd_mega(Args args) {
;     ...
;             for (int i = 0; i < 3; ++i) { const int m = m0 + i * NGW; if (m < MT) { float ss = 0.f;
; #pragma unroll
;                 for (int j = 0; j < 4; ++j) { const f32x4 x = v[i][j]; ss += (x[0] * x[0] + x[1] * x[1]) + (x[2] * x[2] + x[3] * x[3]);
;                     u32x2 w; w.x = pk2(x[0], x[1]); w.y = pk2(x[2], x[3]); *(u32x2*)(XB + (size_t)m * DM + 4 * lane + 256 * j) = w; }
; #pragma unroll
;                 for (int ofs = 1; ofs < 64; ofs <<= 1) ss += __shfl_xor(ss, ofs);
;                 if (lane == 0) RSS[m] = ss; } }
.Lxb_ld_done:
	s_waitcnt vmcnt(0)
	s_mov_b32 s4, s26
	s_cmpk_gt_i32 s4, 0x41ff
	s_cbranch_scc1 .Lxb_next
	s_lshl_b32 s5, s4, 11
	s_add_u32 s18, s10, s5
	s_addc_u32 s19, s11, 0
	s_add_u32 s18, s18, 0x3400000
	s_addc_u32 s19, s19, 0
	s_lshl_b32 s5, s4, 2
	s_add_u32 s20, s2, s5
	s_addc_u32 s21, s3, 0
	v_mul_f32_e32 v135, v1, v1
	v_mul_f32_e32 v75, v3, v3
	v_fmac_f32_e32 v135, v0, v0
	v_fmac_f32_e32 v75, v2, v2
	v_cvt_pk_bf16_f32 v72, v0, v1
	v_cvt_pk_bf16_f32 v73, v2, v3
	v_add_f32_e32 v135, v135, v75
	global_store_dwordx2 v133, v[72:73], s[18:19]
	v_mul_f32_e32 v136, v5, v5
	v_mul_f32_e32 v75, v7, v7
	v_fmac_f32_e32 v136, v4, v4
	v_fmac_f32_e32 v75, v6, v6
	v_cvt_pk_bf16_f32 v72, v4, v5
	v_cvt_pk_bf16_f32 v73, v6, v7
	v_add_f32_e32 v136, v136, v75
	v_add_f32_e32 v135, v135, v136
	global_store_dwordx2 v133, v[72:73], s[18:19] offset:512
	v_mul_f32_e32 v136, v9, v9
	v_mul_f32_e32 v75, v11, v11
	v_fmac_f32_e32 v136, v8, v8
	v_fmac_f32_e32 v75, v10, v10
	v_cvt_pk_bf16_f32 v72, v8, v9
	v_cvt_pk_bf16_f32 v73, v10, v11
	v_add_f32_e32 v136, v136, v75
	v_add_f32_e32 v135, v135, v136
	global_store_dwordx2 v133, v[72:73], s[18:19] offset:1024
	v_mul_f32_e32 v136, v13, v13
	v_mul_f32_e32 v75, v15, v15
	v_fmac_f32_e32 v136, v12, v12
	v_fmac_f32_e32 v75, v14, v14
	v_cvt_pk_bf16_f32 v72, v12, v13
	v_cvt_pk_bf16_f32 v73, v14, v15
	v_add_f32_e32 v136, v136, v75
	v_add_f32_e32 v135, v135, v136
	global_store_dwordx2 v133, v[72:73], s[18:19] offset:1536
	s_nop 1
	v_add_f32_dpp v135, v135, v135 quad_perm:[1,0,3,2] row_mask:0xf bank_mask:0xf
	s_nop 1
	v_add_f32_dpp v135, v135, v135 quad_perm:[2,3,0,1] row_mask:0xf bank_mask:0xf
	s_nop 1
	v_add_f32_dpp v135, v135, v135 row_half_mirror row_mask:0xf bank_mask:0xf
	s_nop 1
	v_add_f32_dpp v135, v135, v135 row_mirror row_mask:0xf bank_mask:0xf
	v_mov_b32_e32 v136, v135
	s_nop 1
	v_permlane16_swap_b32_e32 v135, v136
	v_add_f32_e32 v135, v135, v136
	v_mov_b32_e32 v136, v135
	s_nop 1
	v_permlane32_swap_b32_e32 v135, v136
	v_add_f32_e32 v135, v135, v136
	s_mov_b64 exec, 1
	global_store_dword v134, v135, s[20:21]
	s_mov_b64 exec, -1
	s_add_i32 s4, s4, s82
	s_cmpk_gt_i32 s4, 0x41ff
	s_cbranch_scc1 .Lxb_next
	s_lshl_b32 s5, s4, 11
	s_add_u32 s18, s10, s5
	s_addc_u32 s19, s11, 0
	s_add_u32 s18, s18, 0x3400000
	s_addc_u32 s19, s19, 0
	s_lshl_b32 s5, s4, 2
	s_add_u32 s20, s2, s5
	s_addc_u32 s21, s3, 0
	v_mul_f32_e32 v135, v17, v17
	v_mul_f32_e32 v75, v19, v19
	v_fmac_f32_e32 v135, v16, v16
	v_fmac_f32_e32 v75, v18, v18
	v_cvt_pk_bf16_f32 v72, v16, v17
	v_cvt_pk_bf16_f32 v73, v18, v19
	v_add_f32_e32 v135, v135, v75
	global_store_dwordx2 v133, v[72:73], s[18:19]
	v_mul_f32_e32 v136, v21, v21
	v_mul_f32_e32 v75, v23, v23
	v_fmac_f32_e32 v136, v20, v20
	v_fmac_f32_e32 v75, v22, v22
	v_cvt_pk_bf16_f32 v72, v20, v21
	v_cvt_pk_bf16_f32 v73, v22, v23
	v_add_f32_e32 v136, v136, v75
	v_add_f32_e32 v135, v135, v136
	global_store_dwordx2 v133, v[72:73], s[18:19] offset:512
	v_mul_f32_e32 v136, v25, v25
	v_mul_f32_e32 v75, v27, v27
	v_fmac_f32_e32 v136, v24, v24
	v_fmac_f32_e32 v75, v26, v26
	v_cvt_pk_bf16_f32 v72, v24, v25
	v_cvt_pk_bf16_f32 v73, v26, v27
	v_add_f32_e32 v136, v136, v75
	v_add_f32_e32 v135, v135, v136
	global_store_dwordx2 v133, v[72:73], s[18:19] offset:1024
	v_mul_f32_e32 v136, v29, v29
	v_mul_f32_e32 v75, v31, v31
	v_fmac_f32_e32 v136, v28, v28
	v_fmac_f32_e32 v75, v30, v30
	v_cvt_pk_bf16_f32 v72, v28, v29
	v_cvt_pk_bf16_f32 v73, v30, v31
	v_add_f32_e32 v136, v136, v75
	v_add_f32_e32 v135, v135, v136
	global_store_dwordx2 v133, v[72:73], s[18:19] offset:1536
	s_nop 1
	v_add_f32_dpp v135, v135, v135 quad_perm:[1,0,3,2] row_mask:0xf bank_mask:0xf
	s_nop 1
	v_add_f32_dpp v135, v135, v135 quad_perm:[2,3,0,1] row_mask:0xf bank_mask:0xf
	s_nop 1
	v_add_f32_dpp v135, v135, v135 row_half_mirror row_mask:0xf bank_mask:0xf
	s_nop 1
	v_add_f32_dpp v135, v135, v135 row_mirror row_mask:0xf bank_mask:0xf
	v_mov_b32_e32 v136, v135
	s_nop 1
	v_permlane16_swap_b32_e32 v135, v136
	v_add_f32_e32 v135, v135, v136
	v_mov_b32_e32 v136, v135
	s_nop 1
	v_permlane32_swap_b32_e32 v135, v136
	v_add_f32_e32 v135, v135, v136
	s_mov_b64 exec, 1
	global_store_dword v134, v135, s[20:21]
	s_mov_b64 exec, -1
	s_add_i32 s4, s4, s82
	s_cmpk_gt_i32 s4, 0x41ff
	s_cbranch_scc1 .Lxb_next
	s_lshl_b32 s5, s4, 11
	s_add_u32 s18, s10, s5
	s_addc_u32 s19, s11, 0
	s_add_u32 s18, s18, 0x3400000
	s_addc_u32 s19, s19, 0
	s_lshl_b32 s5, s4, 2
	s_add_u32 s20, s2, s5
	s_addc_u32 s21, s3, 0
	v_mul_f32_e32 v135, v33, v33
	v_mul_f32_e32 v75, v35, v35
	v_fmac_f32_e32 v135, v32, v32
	v_fmac_f32_e32 v75, v34, v34
	v_cvt_pk_bf16_f32 v72, v32, v33
	v_cvt_pk_bf16_f32 v73, v34, v35
	v_add_f32_e32 v135, v135, v75
	global_store_dwordx2 v133, v[72:73], s[18:19]
	v_mul_f32_e32 v136, v37, v37
	v_mul_f32_e32 v75, v39, v39
	v_fmac_f32_e32 v136, v36, v36
	v_fmac_f32_e32 v75, v38, v38
	v_cvt_pk_bf16_f32 v72, v36, v37
	v_cvt_pk_bf16_f32 v73, v38, v39
	v_add_f32_e32 v136, v136, v75
	v_add_f32_e32 v135, v135, v136
	global_store_dwordx2 v133, v[72:73], s[18:19] offset:512
	v_mul_f32_e32 v136, v41, v41
	v_mul_f32_e32 v75, v43, v43
	v_fmac_f32_e32 v136, v40, v40
	v_fmac_f32_e32 v75, v42, v42
	v_cvt_pk_bf16_f32 v72, v40, v41
	v_cvt_pk_bf16_f32 v73, v42, v43
	v_add_f32_e32 v136, v136, v75
	v_add_f32_e32 v135, v135, v136
	global_store_dwordx2 v133, v[72:73], s[18:19] offset:1024
	v_mul_f32_e32 v136, v45, v45
	v_mul_f32_e32 v75, v47, v47
	v_fmac_f32_e32 v136, v44, v44
	v_fmac_f32_e32 v75, v46, v46
	v_cvt_pk_bf16_f32 v72, v44, v45
	v_cvt_pk_bf16_f32 v73, v46, v47
	v_add_f32_e32 v136, v136, v75
	v_add_f32_e32 v135, v135, v136
	global_store_dwordx2 v133, v[72:73], s[18:19] offset:1536
	s_nop 1
	v_add_f32_dpp v135, v135, v135 quad_perm:[1,0,3,2] row_mask:0xf bank_mask:0xf
	s_nop 1
	v_add_f32_dpp v135, v135, v135 quad_perm:[2,3,0,1] row_mask:0xf bank_mask:0xf
	s_nop 1
	v_add_f32_dpp v135, v135, v135 row_half_mirror row_mask:0xf bank_mask:0xf
	s_nop 1
	v_add_f32_dpp v135, v135, v135 row_mirror row_mask:0xf bank_mask:0xf
	v_mov_b32_e32 v136, v135
	s_nop 1
	v_permlane16_swap_b32_e32 v135, v136
	v_add_f32_e32 v135, v135, v136
	v_mov_b32_e32 v136, v135
	s_nop 1
	v_permlane32_swap_b32_e32 v135, v136
	v_add_f32_e32 v135, v135, v136
	s_mov_b64 exec, 1
	global_store_dword v134, v135, s[20:21]
	s_mov_b64 exec, -1
	s_add_i32 s4, s4, s82
	s_cmpk_gt_i32 s4, 0x41ff
	s_cbranch_scc1 .Lxb_next
; __device__ __forceinline__ unsigned pk2(float lo, float hi) { f32x2 v = {lo, hi}; bf16x2_t b = __builtin_convertvector(v, bf16x2_t); return __builtin_bit_cast(unsigned, b); }
; __global__ void __launch_bounds__(NWAVES * 64, 2) fwd_mega(Args args) {
;     ...
;             for (int i = 0; i < 3; ++i) { const int m = m0 + i * NGW; if (m < MT) { float ss = 0.f;
; #pragma unroll
;                 for (int j = 0; j < 4; ++j) { const f32x4 x = v[i][j]; ss += (x[0] * x[0] + x[1] * x[1]) + (x[2] * x[2] + x[3] * x[3]);
;                     u32x2 w; w.x = pk2(x[0], x[1]); w.y = pk2(x[2], x[3]); *(u32x2*)(XB + (size_t)m * DM + 4 * lane + 256 * j) = w; }
; #pragma unroll
;                 for (int ofs = 1; ofs < 64; ofs <<= 1) ss += __shfl_xor(ss, ofs);
;                 if (lane == 0) RSS[m] = ss; } }
	s_lshl_b32 s5, s4, 11
	s_add_u32 s18, s10, s5
	s_addc_u32 s19, s11, 0
	s_add_u32 s18, s18, 0x3400000
	s_addc_u32 s19, s19, 0
	s_lshl_b32 s5, s4, 2
	s_add_u32 s20, s2, s5
	s_addc_u32 s21, s3, 0
	v_mul_f32_e32 v135, v49, v49
	v_mul_f32_e32 v75, v51, v51
	v_fmac_f32_e32 v135, v48, v48
	v_fmac_f32_e32 v75, v50, v50
	v_cvt_pk_bf16_f32 v72, v48, v49
	v_cvt_pk_bf16_f32 v73, v50, v51
	v_add_f32_e32 v135, v135, v75
	global_store_dwordx2 v133, v[72:73], s[18:19]
	v_mul_f32_e32 v136, v53, v53
	v_mul_f32_e32 v75, v55, v55
	v_fmac_f32_e32 v136, v52, v52
	v_fmac_f32_e32 v75, v54, v54
	v_cvt_pk_bf16_f32 v72, v52, v53
	v_cvt_pk_bf16_f32 v73, v54, v55
	v_add_f32_e32 v136, v136, v75
	v_add_f32_e32 v135, v135, v136
	global_store_dwordx2 v133, v[72:73], s[18:19] offset:512
	v_mul_f32_e32 v136, v57, v57
	v_mul_f32_e32 v75, v59, v59
	v_fmac_f32_e32 v136, v56, v56
	v_fmac_f32_e32 v75, v58, v58
	v_cvt_pk_bf16_f32 v72, v56, v57
	v_cvt_pk_bf16_f32 v73, v58, v59
	v_add_f32_e32 v136, v136, v75
	v_add_f32_e32 v135, v135, v136
	global_store_dwordx2 v133, v[72:73], s[18:19] offset:1024
	v_mul_f32_e32 v136, v61, v61
	v_mul_f32_e32 v75, v63, v63
	v_fmac_f32_e32 v136, v60, v60
	v_fmac_f32_e32 v75, v62, v62
	v_cvt_pk_bf16_f32 v72, v60, v61
	v_cvt_pk_bf16_f32 v73, v62, v63
	v_add_f32_e32 v136, v136, v75
	v_add_f32_e32 v135, v135, v136
	global_store_dwordx2 v133, v[72:73], s[18:19] offset:1536
	s_nop 1
	v_add_f32_dpp v135, v135, v135 quad_perm:[1,0,3,2] row_mask:0xf bank_mask:0xf
	s_nop 1
	v_add_f32_dpp v135, v135, v135 quad_perm:[2,3,0,1] row_mask:0xf bank_mask:0xf
	s_nop 1
	v_add_f32_dpp v135, v135, v135 row_half_mirror row_mask:0xf bank_mask:0xf
	s_nop 1
	v_add_f32_dpp v135, v135, v135 row_mirror row_mask:0xf bank_mask:0xf
	v_mov_b32_e32 v136, v135
	s_nop 1
	v_permlane16_swap_b32_e32 v135, v136
	v_add_f32_e32 v135, v135, v136
	v_mov_b32_e32 v136, v135
	s_nop 1
	v_permlane32_swap_b32_e32 v135, v136
	v_add_f32_e32 v135, v135, v136
	s_mov_b64 exec, 1
	global_store_dword v134, v135, s[20:21]
	s_mov_b64 exec, -1
	s_add_i32 s4, s4, s82
	s_cmpk_gt_i32 s4, 0x41ff
	s_cbranch_scc1 .Lxb_next
	s_lshl_b32 s5, s4, 11
	s_add_u32 s18, s10, s5
	s_addc_u32 s19, s11, 0
	s_add_u32 s18, s18, 0x3400000
	s_addc_u32 s19, s19, 0
	s_lshl_b32 s5, s4, 2
	s_add_u32 s20, s2, s5
	s_addc_u32 s21, s3, 0
	v_mul_f32_e32 v135, v65, v65
	v_mul_f32_e32 v75, v67, v67
	v_fmac_f32_e32 v135, v64, v64
	v_fmac_f32_e32 v75, v66, v66
	v_cvt_pk_bf16_f32 v72, v64, v65
	v_cvt_pk_bf16_f32 v73, v66, v67
	v_add_f32_e32 v135, v135, v75
	global_store_dwordx2 v133, v[72:73], s[18:19]
	v_mul_f32_e32 v136, v69, v69
	v_mul_f32_e32 v75, v71, v71
	v_fmac_f32_e32 v136, v68, v68
	v_fmac_f32_e32 v75, v70, v70
	v_cvt_pk_bf16_f32 v72, v68, v69
	v_cvt_pk_bf16_f32 v73, v70, v71
	v_add_f32_e32 v136, v136, v75
	v_add_f32_e32 v135, v135, v136
	global_store_dwordx2 v133, v[72:73], s[18:19] offset:512
	v_mul_f32_e32 v136, v77, v77
	v_mul_f32_e32 v75, v79, v79
	v_fmac_f32_e32 v136, v76, v76
	v_fmac_f32_e32 v75, v78, v78
	v_cvt_pk_bf16_f32 v72, v76, v77
	v_cvt_pk_bf16_f32 v73, v78, v79
	v_add_f32_e32 v136, v136, v75
	v_add_f32_e32 v135, v135, v136
	global_store_dwordx2 v133, v[72:73], s[18:19] offset:1024
	v_mul_f32_e32 v136, v81, v81
	v_mul_f32_e32 v75, v83, v83
	v_fmac_f32_e32 v136, v80, v80
	v_fmac_f32_e32 v75, v82, v82
	v_cvt_pk_bf16_f32 v72, v80, v81
	v_cvt_pk_bf16_f32 v73, v82, v83
	v_add_f32_e32 v136, v136, v75
	v_add_f32_e32 v135, v135, v136
	global_store_dwordx2 v133, v[72:73], s[18:19] offset:1536
	s_nop 1
	v_add_f32_dpp v135, v135, v135 quad_perm:[1,0,3,2] row_mask:0xf bank_mask:0xf
	s_nop 1
	v_add_f32_dpp v135, v135, v135 quad_perm:[2,3,0,1] row_mask:0xf bank_mask:0xf
	s_nop 1
	v_add_f32_dpp v135, v135, v135 row_half_mirror row_mask:0xf bank_mask:0xf
	s_nop 1
	v_add_f32_dpp v135, v135, v135 row_mirror row_mask:0xf bank_mask:0xf
	v_mov_b32_e32 v136, v135
	s_nop 1
	v_permlane16_swap_b32_e32 v135, v136
	v_add_f32_e32 v135, v135, v136
	v_mov_b32_e32 v136, v135
	s_nop 1
	v_permlane32_swap_b32_e32 v135, v136
	v_add_f32_e32 v135, v135, v136
	s_mov_b64 exec, 1
	global_store_dword v134, v135, s[20:21]
	s_mov_b64 exec, -1
	s_add_i32 s4, s4, s82
	s_cmpk_gt_i32 s4, 0x41ff
	s_cbranch_scc1 .Lxb_next
	s_lshl_b32 s5, s4, 11
	s_add_u32 s18, s10, s5
	s_addc_u32 s19, s11, 0
	s_add_u32 s18, s18, 0x3400000
	s_addc_u32 s19, s19, 0
	s_lshl_b32 s5, s4, 2
	s_add_u32 s20, s2, s5
	s_addc_u32 s21, s3, 0
	v_mul_f32_e32 v135, v85, v85
	v_mul_f32_e32 v75, v87, v87
	v_fmac_f32_e32 v135, v84, v84
	v_fmac_f32_e32 v75, v86, v86
	v_cvt_pk_bf16_f32 v72, v84, v85
	v_cvt_pk_bf16_f32 v73, v86, v87
	v_add_f32_e32 v135, v135, v75
	global_store_dwordx2 v133, v[72:73], s[18:19]
	v_mul_f32_e32 v136, v89, v89
	v_mul_f32_e32 v75, v91, v91
	v_fmac_f32_e32 v136, v88, v88
	v_fmac_f32_e32 v75, v90, v90
	v_cvt_pk_bf16_f32 v72, v88, v89
	v_cvt_pk_bf16_f32 v73, v90, v91
	v_add_f32_e32 v136, v136, v75
	v_add_f32_e32 v135, v135, v136
	global_store_dwordx2 v133, v[72:73], s[18:19] offset:512
	v_mul_f32_e32 v136, v93, v93
	v_mul_f32_e32 v75, v95, v95
	v_fmac_f32_e32 v136, v92, v92
	v_fmac_f32_e32 v75, v94, v94
	v_cvt_pk_bf16_f32 v72, v92, v93
	v_cvt_pk_bf16_f32 v73, v94, v95
	v_add_f32_e32 v136, v136, v75
	v_add_f32_e32 v135, v135, v136
	global_store_dwordx2 v133, v[72:73], s[18:19] offset:1024
	v_mul_f32_e32 v136, v97, v97
	v_mul_f32_e32 v75, v99, v99
	v_fmac_f32_e32 v136, v96, v96
	v_fmac_f32_e32 v75, v98, v98
	v_cvt_pk_bf16_f32 v72, v96, v97
	v_cvt_pk_bf16_f32 v73, v98, v99
	v_add_f32_e32 v136, v136, v75
	v_add_f32_e32 v135, v135, v136
	global_store_dwordx2 v133, v[72:73], s[18:19] offset:1536
	s_nop 1
	v_add_f32_dpp v135, v135, v135 quad_perm:[1,0,3,2] row_mask:0xf bank_mask:0xf
	s_nop 1
	v_add_f32_dpp v135, v135, v135 quad_perm:[2,3,0,1] row_mask:0xf bank_mask:0xf
	s_nop 1
	v_add_f32_dpp v135, v135, v135 row_half_mirror row_mask:0xf bank_mask:0xf
	s_nop 1
	v_add_f32_dpp v135, v135, v135 row_mirror row_mask:0xf bank_mask:0xf
	v_mov_b32_e32 v136, v135
	s_nop 1
	v_permlane16_swap_b32_e32 v135, v136
	v_add_f32_e32 v135, v135, v136
	v_mov_b32_e32 v136, v135
	s_nop 1
	v_permlane32_swap_b32_e32 v135, v136
	v_add_f32_e32 v135, v135, v136
	s_mov_b64 exec, 1
	global_store_dword v134, v135, s[20:21]
	s_mov_b64 exec, -1
	s_add_i32 s4, s4, s82
	s_cmpk_gt_i32 s4, 0x41ff
	s_cbranch_scc1 .Lxb_next
; __device__ __forceinline__ unsigned pk2(float lo, float hi) { f32x2 v = {lo, hi}; bf16x2_t b = __builtin_convertvector(v, bf16x2_t); return __builtin_bit_cast(unsigned, b); }
; __global__ void __launch_bounds__(NWAVES * 64, 2) fwd_mega(Args args) {
;     ...
;             for (int i = 0; i < 3; ++i) { const int m = m0 + i * NGW; if (m < MT) { float ss = 0.f;
; #pragma unroll
;                 for (int j = 0; j < 4; ++j) { const f32x4 x = v[i][j]; ss += (x[0] * x[0] + x[1] * x[1]) + (x[2] * x[2] + x[3] * x[3]);
;                     u32x2 w; w.x = pk2(x[0], x[1]); w.y = pk2(x[2], x[3]); *(u32x2*)(XB + (size_t)m * DM + 4 * lane + 256 * j) = w; }
; #pragma unroll
;                 for (int ofs = 1; ofs < 64; ofs <<= 1) ss += __shfl_xor(ss, ofs);
;                 if (lane == 0) RSS[m] = ss; } }
	s_lshl_b32 s5, s4, 11
	s_add_u32 s18, s10, s5
	s_addc_u32 s19, s11, 0
	s_add_u32 s18, s18, 0x3400000
	s_addc_u32 s19, s19, 0
	s_lshl_b32 s5, s4, 2
	s_add_u32 s20, s2, s5
	s_addc_u32 s21, s3, 0
	v_mul_f32_e32 v135, v101, v101
	v_mul_f32_e32 v75, v103, v103
	v_fmac_f32_e32 v135, v100, v100
	v_fmac_f32_e32 v75, v102, v102
	v_cvt_pk_bf16_f32 v72, v100, v101
	v_cvt_pk_bf16_f32 v73, v102, v103
	v_add_f32_e32 v135, v135, v75
	global_store_dwordx2 v133, v[72:73], s[18:19]
	v_mul_f32_e32 v136, v105, v105
	v_mul_f32_e32 v75, v107, v107
	v_fmac_f32_e32 v136, v104, v104
	v_fmac_f32_e32 v75, v106, v106
	v_cvt_pk_bf16_f32 v72, v104, v105
	v_cvt_pk_bf16_f32 v73, v106, v107
	v_add_f32_e32 v136, v136, v75
	v_add_f32_e32 v135, v135, v136
	global_store_dwordx2 v133, v[72:73], s[18:19] offset:512
	v_mul_f32_e32 v136, v109, v109
	v_mul_f32_e32 v75, v111, v111
	v_fmac_f32_e32 v136, v108, v108
	v_fmac_f32_e32 v75, v110, v110
	v_cvt_pk_bf16_f32 v72, v108, v109
	v_cvt_pk_bf16_f32 v73, v110, v111
	v_add_f32_e32 v136, v136, v75
	v_add_f32_e32 v135, v135, v136
	global_store_dwordx2 v133, v[72:73], s[18:19] offset:1024
	v_mul_f32_e32 v136, v113, v113
	v_mul_f32_e32 v75, v115, v115
	v_fmac_f32_e32 v136, v112, v112
	v_fmac_f32_e32 v75, v114, v114
	v_cvt_pk_bf16_f32 v72, v112, v113
	v_cvt_pk_bf16_f32 v73, v114, v115
	v_add_f32_e32 v136, v136, v75
	v_add_f32_e32 v135, v135, v136
	global_store_dwordx2 v133, v[72:73], s[18:19] offset:1536
	s_nop 1
	v_add_f32_dpp v135, v135, v135 quad_perm:[1,0,3,2] row_mask:0xf bank_mask:0xf
	s_nop 1
	v_add_f32_dpp v135, v135, v135 quad_perm:[2,3,0,1] row_mask:0xf bank_mask:0xf
	s_nop 1
	v_add_f32_dpp v135, v135, v135 row_half_mirror row_mask:0xf bank_mask:0xf
	s_nop 1
	v_add_f32_dpp v135, v135, v135 row_mirror row_mask:0xf bank_mask:0xf
	v_mov_b32_e32 v136, v135
	s_nop 1
	v_permlane16_swap_b32_e32 v135, v136
	v_add_f32_e32 v135, v135, v136
	v_mov_b32_e32 v136, v135
	s_nop 1
	v_permlane32_swap_b32_e32 v135, v136
	v_add_f32_e32 v135, v135, v136
	s_mov_b64 exec, 1
	global_store_dword v134, v135, s[20:21]
	s_mov_b64 exec, -1
	s_add_i32 s4, s4, s82
	s_cmpk_gt_i32 s4, 0x41ff
	s_cbranch_scc1 .Lxb_next
	s_lshl_b32 s5, s4, 11
	s_add_u32 s18, s10, s5
	s_addc_u32 s19, s11, 0
	s_add_u32 s18, s18, 0x3400000
	s_addc_u32 s19, s19, 0
	s_lshl_b32 s5, s4, 2
	s_add_u32 s20, s2, s5
	s_addc_u32 s21, s3, 0
	v_mul_f32_e32 v135, v117, v117
	v_mul_f32_e32 v75, v119, v119
	v_fmac_f32_e32 v135, v116, v116
	v_fmac_f32_e32 v75, v118, v118
	v_cvt_pk_bf16_f32 v72, v116, v117
	v_cvt_pk_bf16_f32 v73, v118, v119
	v_add_f32_e32 v135, v135, v75
	global_store_dwordx2 v133, v[72:73], s[18:19]
	v_mul_f32_e32 v136, v121, v121
	v_mul_f32_e32 v75, v123, v123
	v_fmac_f32_e32 v136, v120, v120
	v_fmac_f32_e32 v75, v122, v122
	v_cvt_pk_bf16_f32 v72, v120, v121
	v_cvt_pk_bf16_f32 v73, v122, v123
	v_add_f32_e32 v136, v136, v75
	v_add_f32_e32 v135, v135, v136
	global_store_dwordx2 v133, v[72:73], s[18:19] offset:512
	v_mul_f32_e32 v136, v125, v125
	v_mul_f32_e32 v75, v127, v127
	v_fmac_f32_e32 v136, v124, v124
	v_fmac_f32_e32 v75, v126, v126
	v_cvt_pk_bf16_f32 v72, v124, v125
	v_cvt_pk_bf16_f32 v73, v126, v127
	v_add_f32_e32 v136, v136, v75
	v_add_f32_e32 v135, v135, v136
	global_store_dwordx2 v133, v[72:73], s[18:19] offset:1024
	v_mul_f32_e32 v136, v129, v129
	v_mul_f32_e32 v75, v131, v131
	v_fmac_f32_e32 v136, v128, v128
	v_fmac_f32_e32 v75, v130, v130
	v_cvt_pk_bf16_f32 v72, v128, v129
	v_cvt_pk_bf16_f32 v73, v130, v131
	v_add_f32_e32 v136, v136, v75
	v_add_f32_e32 v135, v135, v136
	global_store_dwordx2 v133, v[72:73], s[18:19] offset:1536
	s_nop 1
	v_add_f32_dpp v135, v135, v135 quad_perm:[1,0,3,2] row_mask:0xf bank_mask:0xf
	s_nop 1
	v_add_f32_dpp v135, v135, v135 quad_perm:[2,3,0,1] row_mask:0xf bank_mask:0xf
	s_nop 1
	v_add_f32_dpp v135, v135, v135 row_half_mirror row_mask:0xf bank_mask:0xf
	s_nop 1
	v_add_f32_dpp v135, v135, v135 row_mirror row_mask:0xf bank_mask:0xf
	v_mov_b32_e32 v136, v135
	s_nop 1
	v_permlane16_swap_b32_e32 v135, v136
	v_add_f32_e32 v135, v135, v136
	v_mov_b32_e32 v136, v135
	s_nop 1
	v_permlane32_swap_b32_e32 v135, v136
	v_add_f32_e32 v135, v135, v136
	s_mov_b64 exec, 1
	global_store_dword v134, v135, s[20:21]
	s_mov_b64 exec, -1
	s_add_i32 s4, s4, s82
.Lxb_next:
	s_lshl_b32 s5, s82, 3
	s_add_i32 s26, s26, s5
	s_branch .Lxb_batch

; __device__ __forceinline__ unsigned pk2(float lo, float hi) { f32x2 v = {lo, hi}; bf16x2_t b = __builtin_convertvector(v, bf16x2_t); return __builtin_bit_cast(unsigned, b); }
; #define KIN(i) ((const float*)kptr<float>(i))
; __global__ void __launch_bounds__(NWAVES * 64, 2) fwd_mega(Args args) {
;     ...
;         { const float* x_prompt = KIN(0); const float* x_sample = KIN(1); bf16_t* XB = (bf16_t*)(ws + WS_XB); float* RSS = (float*)(ws + WS_RSS);
;         for (int m0 = gw; m0 < MT; m0 += 3 * NGW) {
;             f32x4 v[3][4];
; #pragma unroll
;             for (int i = 0; i < 3; ++i) { const int m = m0 + i * NGW; if (m < MT) { const float* src = m < TP ? x_prompt + (size_t)m * DM : x_sample + (size_t)(m - TP) * DM;
; #pragma unroll
;                 for (int j = 0; j < 4; ++j) v[i][j] = __builtin_nontemporal_load((const f32x4*)(src + 4 * lane + 256 * j)); } }
; #pragma unroll
;             for (int i = 0; i < 3; ++i) { const int m = m0 + i * NGW; if (m < MT) { float ss = 0.f;
; #pragma unroll
;                 for (int j = 0; j < 4; ++j) { const f32x4 x = v[i][j]; ss += (x[0] * x[0] + x[1] * x[1]) + (x[2] * x[2] + x[3] * x[3]);
;                     u32x2 w; w.x = pk2(x[0], x[1]); w.y = pk2(x[2], x[3]); *(u32x2*)(XB + (size_t)m * DM + 4 * lane + 256 * j) = w; }
; #pragma unroll
;                 for (int ofs = 1; ofs < 64; ofs <<= 1) ss += __shfl_xor(ss, ofs);
;                 if (lane == 0) RSS[m] = ss; } }
.Lx_nosplit:
	v_mov_b32_e32 v49, 0
	v_lshlrev_b32_e32 v48, 3, v0
	v_lshl_add_u64 v[4:5], s[10:11], 0, v[48:49]
	s_mov_b64 s[4:5], 0x3400000
	v_lshlrev_b32_e32 v2, 2, v0
	v_lshl_add_u64 v[50:51], v[4:5], 0, s[4:5]
	v_cmp_eq_u32_e64 s[4:5], 0, v0
	v_mbcnt_lo_u32_b32 v0, -1, 0
	v_mbcnt_hi_u32_b32 v0, -1, v0
	v_and_b32_e32 v1, 64, v0
	v_add_u32_e32 v1, 64, v1
	v_xor_b32_e32 v3, 1, v0
	v_cmp_lt_i32_e32 vcc, v3, v1
	s_add_i32 s28, s26, 0xffffc000
	s_mul_i32 s29, s82, 3
	v_cndmask_b32_e32 v3, v0, v3, vcc
	v_lshlrev_b32_e32 v48, 2, v3
	v_xor_b32_e32 v3, 2, v0
	v_cmp_lt_i32_e32 vcc, v3, v1
	s_lshl_b32 s30, s82, 1
	v_lshlrev_b32_e32 v57, 2, v2
	v_cndmask_b32_e32 v3, v0, v3, vcc
	v_lshlrev_b32_e32 v52, 2, v3
	v_xor_b32_e32 v3, 4, v0
	v_cmp_lt_i32_e32 vcc, v3, v1
	s_nop 1
	v_cndmask_b32_e32 v3, v0, v3, vcc
	v_lshlrev_b32_e32 v53, 2, v3
	v_xor_b32_e32 v3, 8, v0
	v_cmp_lt_i32_e32 vcc, v3, v1
	s_nop 1
	v_cndmask_b32_e32 v3, v0, v3, vcc
	v_lshlrev_b32_e32 v54, 2, v3
	v_xor_b32_e32 v3, 16, v0
	v_cmp_lt_i32_e32 vcc, v3, v1
	s_nop 1
	v_cndmask_b32_e32 v3, v0, v3, vcc
	v_lshlrev_b32_e32 v55, 2, v3
	v_xor_b32_e32 v3, 32, v0
	v_cmp_lt_i32_e32 vcc, v3, v1
	s_nop 1
	v_cndmask_b32_e32 v0, v0, v3, vcc
	v_lshlrev_b32_e32 v56, 2, v0
	s_branch .LBB0_47

; __global__ void __launch_bounds__(NWAVES * 64, 2) fwd_mega(Args args) {
;     ...
;         const int gt = blockIdx.x * (NWAVES * 64) + tid, NGT = G * NWAVES * 64;
;         for (int i = gt; i < 3 * MT; i += NGT) RSS[MT + i] = 0.f;
.LBB0_60:
	s_lshl_b32 s82, s33, 3
	v_lshl_add_u32 v0, s76, 9, v74
	s_mov_b32 s4, 0xc600
	s_lshl_b32 s12, s33, 9
	v_cmp_gt_i32_e32 vcc, s4, v0
	s_and_saveexec_b64 s[14:15], vcc
	s_cbranch_execz .LBB0_68
	v_cvt_f32_u32_e32 v2, s12
	v_add_u32_e32 v1, s12, v0
	v_mov_b32_e32 v3, s12
	v_cmp_gt_i32_e32 vcc, s4, v1
	v_rcp_iflag_f32_e32 v2, v2
	s_sub_i32 s13, 0, s12
	v_max_i32_e32 v4, 0xc600, v1
	v_addc_co_u32_e64 v3, s[4:5], v0, v3, vcc
	v_mul_f32_e32 v2, 0x4f7ffffe, v2
	v_cvt_u32_f32_e32 v2, v2
	v_sub_u32_e32 v3, v4, v3
	v_mul_lo_u32 v4, s13, v2
	v_mul_hi_u32 v4, v2, v4
	v_add_u32_e32 v2, v2, v4
	v_mul_hi_u32 v2, v3, v2
	v_mul_lo_u32 v4, v2, s12
	v_sub_u32_e32 v3, v3, v4
	v_add_u32_e32 v5, 1, v2
	v_cmp_le_u32_e64 s[4:5], s12, v3
	v_subrev_u32_e32 v4, s12, v3
	s_nop 0
	v_cndmask_b32_e64 v2, v2, v5, s[4:5]
	v_cndmask_b32_e64 v3, v3, v4, s[4:5]
	v_add_u32_e32 v4, 1, v2
	v_cmp_le_u32_e64 s[4:5], s12, v3
	s_nop 1
	v_cndmask_b32_e64 v2, v2, v4, s[4:5]
	v_addc_co_u32_e32 v4, vcc, 1, v2, vcc
	v_cmp_lt_u32_e32 vcc, 1, v4
	s_mov_b64 s[4:5], -1
	v_mov_b32_e32 v2, v0
	s_and_saveexec_b64 s[16:17], vcc
	s_cbranch_execz .LBB0_65
	v_and_b32_e32 v5, -2, v4
	s_lshl_b32 s13, s33, 10
	s_mov_b32 s20, s13
	s_mov_b64 s[18:19], 0
	v_mov_b32_e32 v6, 0
	v_mov_b32_e32 v7, v5
	v_mov_b64_e32 v[2:3], v[0:1]
